# attention: next-unit Q touch issued at the start of the epilogue (counted waits leave it in flight)
# speedup vs baseline: 1.0019x; 1.0012x over previous
.LBB0_215:
	s_and_saveexec_b64 s[0:1], s[44:45]
	v_readlane_b32 s2, v254, 53
	s_nop 1
	v_mov_b32_e32 v92, s2
	ds_write_b32 v92, v121 offset:8
	s_or_b64 exec, exec, s[0:1]
	s_waitcnt lgkmcnt(0)
	s_waitcnt vmcnt(0)
	s_barrier
	v_readlane_b32 s2, v254, 53
	s_nop 1
	v_mov_b32_e32 v93, s2
	ds_read_b32 v93, v93 offset:8
	v_mov_b32_e32 v32, v146
	v_mov_b32_e32 v33, v121
	s_and_saveexec_b64 s[0:1], s[44:45]
	s_cbranch_execz .LBB0_219
	s_mov_b64 s[22:23], exec
	v_mbcnt_lo_u32_b32 v32, s22, 0
	v_mbcnt_hi_u32_b32 v32, s23, v32
	v_cmp_eq_u32_e32 vcc, 0, v32
	s_and_saveexec_b64 s[2:3], vcc
	s_cbranch_execz .LBB0_218
	s_bcnt1_i32_b64 s4, s[22:23]
	v_mov_b32_e32 v33, s4
	global_atomic_add v33, v65, v33, s[76:77] sc0

.LBB0_221:
	s_or_b64 exec, exec, s[0:1]
	s_waitcnt lgkmcnt(0)
	v_lshl_add_u32 v34, v151, 2, s79
	ds_read_b128 v[38:41], v34
	ds_read_b128 v[42:45], v34 offset:32
	ds_read_b128 v[46:49], v34 offset:64
	ds_read_b128 v[50:53], v34 offset:96
	v_lshlrev_b32_e32 v90, 4, v148
	v_and_b32_e32 v90, 48, v90
	v_lshlrev_b32_e32 v90, 2, v90
	global_load_dwordx4 v[74:77], v90, s[52:53]
	global_load_dwordx4 v[78:81], v90, s[52:53] offset:32
	global_load_dwordx4 v[82:85], v90, s[52:53] offset:16
	global_load_dwordx4 v[86:89], v90, s[52:53] offset:48
	s_waitcnt lgkmcnt(0)
	v_lshrrev_b32_e32 v94, 2, v93
	v_and_b32_e32 v95, 15, v93
	v_and_b32_e32 v94, -4, v94
	v_mov_b32_e32 v96, 0x405132
	v_lshrrev_b32_e32 v94, v94, v96
	v_readlane_b32 vcc_lo, v254, 37
	v_lshlrev_b32_e32 v95, 7, v95
	v_and_b32_e32 v94, 7, v94
	v_readlane_b32 vcc_hi, v251, 13
	v_or_b32_e32 v95, v95, v149
	v_or_b32_e32 v95, vcc_lo, v95
	v_or_b32_e32 v95, s33, v95
	v_lshlrev_b32_e32 v94, 7, v94
	v_bfe_u32 v97, v148, 5, 1
	v_mov_b32_e32 v96, 0x1080
	v_lshl_add_u32 v94, vcc_hi, 1, v94
	v_mov_b64_e32 v[98:99], s[72:73]
	v_lshl_add_u32 v94, v97, 4, v94
	v_mad_u64_u32 v[98:99], vcc, v95, v96, v[98:99]
	v_mov_b32_e32 v95, 0
	s_nop 0
	v_lshl_add_u64 v[98:99], v[98:99], 0, v[94:95]
	global_load_dwordx4 v[100:103], v[98:99], off
	global_load_dwordx4 v[104:107], v[98:99], off offset:32
	v_lshlrev_b32_e32 v37, 2, v149
	v_readlane_b32 s0, v251, 19
	s_waitcnt lgkmcnt(0)
	v_readlane_b32 s1, v254, 37
	v_mul_f32_e32 v54, v16, v38
	v_mul_f32_e32 v55, v0, v38
	v_or_b32_e32 v56, s1, v151
	v_mul_u32_u24_e32 v56, 0x110, v56
	v_add3_u32 v56, s0, v56, v37
	ds_write2_b32 v56, v54, v55 offset1:32
	v_readlane_b32 s1, v254, 23
	v_mul_f32_e32 v57, v17, v39
	v_mul_f32_e32 v58, v1, v39
	v_or_b32_e32 v59, s1, v151
	v_mul_u32_u24_e32 v59, 0x110, v59
	v_add3_u32 v59, s0, v59, v37
	ds_write2_b32 v59, v57, v58 offset1:32
	v_readlane_b32 s1, v254, 24
	v_mul_f32_e32 v54, v18, v40
	v_mul_f32_e32 v55, v2, v40
	v_or_b32_e32 v56, s1, v151
	v_mul_u32_u24_e32 v56, 0x110, v56
	v_add3_u32 v56, s0, v56, v37
	ds_write2_b32 v56, v54, v55 offset1:32
	v_readlane_b32 s1, v254, 25
	v_mul_f32_e32 v57, v19, v41
	v_mul_f32_e32 v58, v3, v41
	v_or_b32_e32 v59, s1, v151
	v_mul_u32_u24_e32 v59, 0x110, v59
	v_add3_u32 v59, s0, v59, v37
	ds_write2_b32 v59, v57, v58 offset1:32
	v_readlane_b32 s1, v254, 26
	v_mul_f32_e32 v54, v20, v42
	v_mul_f32_e32 v55, v4, v42
	v_or_b32_e32 v56, s1, v151
	v_mul_u32_u24_e32 v56, 0x110, v56
	v_add3_u32 v56, s0, v56, v37
	ds_write2_b32 v56, v54, v55 offset1:32
	v_readlane_b32 s1, v254, 27
	v_mul_f32_e32 v57, v21, v43
	v_mul_f32_e32 v58, v5, v43
	v_or_b32_e32 v59, s1, v151
	v_mul_u32_u24_e32 v59, 0x110, v59
	v_add3_u32 v59, s0, v59, v37
	ds_write2_b32 v59, v57, v58 offset1:32
	v_readlane_b32 s1, v254, 28
	v_mul_f32_e32 v54, v22, v44
	v_mul_f32_e32 v55, v6, v44
	v_or_b32_e32 v56, s1, v151
	v_mul_u32_u24_e32 v56, 0x110, v56
	v_add3_u32 v56, s0, v56, v37
	ds_write2_b32 v56, v54, v55 offset1:32
	v_readlane_b32 s1, v254, 29
	v_mul_f32_e32 v57, v23, v45
	v_mul_f32_e32 v58, v7, v45
	v_or_b32_e32 v59, s1, v151
	v_mul_u32_u24_e32 v59, 0x110, v59
	v_add3_u32 v59, s0, v59, v37
	ds_write2_b32 v59, v57, v58 offset1:32
	v_readlane_b32 s1, v254, 30
	v_mul_f32_e32 v54, v24, v46
	v_mul_f32_e32 v55, v8, v46
	v_or_b32_e32 v56, s1, v151
	v_mul_u32_u24_e32 v56, 0x110, v56
	v_add3_u32 v56, s0, v56, v37
	ds_write2_b32 v56, v54, v55 offset1:32
	v_readlane_b32 s1, v254, 31
	v_mul_f32_e32 v57, v25, v47
	v_mul_f32_e32 v58, v9, v47
	v_or_b32_e32 v59, s1, v151
	v_mul_u32_u24_e32 v59, 0x110, v59
	v_add3_u32 v59, s0, v59, v37
	ds_write2_b32 v59, v57, v58 offset1:32
	v_readlane_b32 s1, v254, 32
	v_mul_f32_e32 v54, v26, v48
	v_mul_f32_e32 v55, v10, v48
	v_or_b32_e32 v56, s1, v151
	v_mul_u32_u24_e32 v56, 0x110, v56
	v_add3_u32 v56, s0, v56, v37
	ds_write2_b32 v56, v54, v55 offset1:32
	v_readlane_b32 s1, v254, 33
	v_mul_f32_e32 v57, v27, v49
	v_mul_f32_e32 v58, v11, v49
	v_or_b32_e32 v59, s1, v151
	v_mul_u32_u24_e32 v59, 0x110, v59
	v_add3_u32 v59, s0, v59, v37
	ds_write2_b32 v59, v57, v58 offset1:32
	v_readlane_b32 s1, v254, 34
	v_mul_f32_e32 v54, v28, v50
	v_mul_f32_e32 v55, v12, v50
	v_or_b32_e32 v56, s1, v151
	v_mul_u32_u24_e32 v56, 0x110, v56
	v_add3_u32 v56, s0, v56, v37
	ds_write2_b32 v56, v54, v55 offset1:32
	v_readlane_b32 s1, v254, 35
	v_mul_f32_e32 v57, v29, v51
	v_mul_f32_e32 v58, v13, v51
	v_or_b32_e32 v59, s1, v151
	v_mul_u32_u24_e32 v59, 0x110, v59
	v_add3_u32 v59, s0, v59, v37
	ds_write2_b32 v59, v57, v58 offset1:32
	v_readlane_b32 s1, v254, 36
	v_mul_f32_e32 v54, v30, v52
	v_mul_f32_e32 v55, v14, v52
	v_or_b32_e32 v56, s1, v151
	v_mul_u32_u24_e32 v56, 0x110, v56
	v_add3_u32 v56, s0, v56, v37
	ds_write2_b32 v56, v54, v55 offset1:32
	v_readlane_b32 s1, v254, 38
	v_mul_f32_e32 v57, v31, v53
	v_mul_f32_e32 v58, v15, v53
	v_or_b32_e32 v59, s1, v151
	v_mul_u32_u24_e32 v59, 0x110, v59
	v_add3_u32 v59, s0, v59, v37
	ds_write2_b32 v59, v57, v58 offset1:32
	v_ashrrev_i32_e32 v50, 2, v148
	v_lshlrev_b32_e32 v0, 4, v148
	v_and_b32_e32 v52, 48, v0
	v_lshlrev_b32_e32 v16, 2, v52
	s_waitcnt lgkmcnt(0)
	s_barrier
	s_movk_i32 s0, 0x110
	v_mul_lo_u32 v17, v50, s0
	v_add3_u32 v46, 0, v17, v16
	ds_read_b128 v[16:19], v46 offset:32
	ds_read_b128 v[20:23], v46 offset:48
	ds_read_b128 v[24:27], v46 offset:34864
	ds_read_b128 v[28:31], v46
	ds_read_b128 v[34:37], v46 offset:16
	ds_read_b128 v[38:41], v46 offset:34832
	ds_read_b128 v[42:45], v46 offset:34848
	ds_read_b128 v[46:49], v46 offset:34816
	s_waitcnt lgkmcnt(5)
	v_pk_fma_f32 v[20:21], v[110:111], v[24:25], v[20:21] neg_lo:[1,0,0] neg_hi:[1,0,0]
	v_pk_fma_f32 v[22:23], v[110:111], v[26:27], v[22:23] neg_lo:[1,0,0] neg_hi:[1,0,0]
	s_waitcnt lgkmcnt(2)
	v_pk_fma_f32 v[34:35], v[110:111], v[38:39], v[34:35] neg_lo:[1,0,0] neg_hi:[1,0,0]
	v_pk_fma_f32 v[36:37], v[110:111], v[40:41], v[36:37] neg_lo:[1,0,0] neg_hi:[1,0,0]
	s_waitcnt lgkmcnt(0)
	v_pk_fma_f32 v[28:29], v[110:111], v[46:47], v[28:29] neg_lo:[1,0,0] neg_hi:[1,0,0]
	v_pk_fma_f32 v[30:31], v[110:111], v[48:49], v[30:31] neg_lo:[1,0,0] neg_hi:[1,0,0]
	v_pk_mul_f32 v[46:47], v[28:29], v[28:29]
	v_pk_mul_f32 v[48:49], v[30:31], v[30:31]
	v_add_f32_e32 v46, v46, v47
	v_add_f32_e32 v46, v46, v48
	v_pk_mul_f32 v[38:39], v[34:35], v[34:35]
	v_add_f32_e32 v46, v46, v49
	v_add_f32_e32 v38, v46, v38
	v_pk_mul_f32 v[40:41], v[36:37], v[36:37]
	v_add_f32_e32 v38, v38, v39
	v_pk_fma_f32 v[16:17], v[110:111], v[42:43], v[16:17] neg_lo:[1,0,0] neg_hi:[1,0,0]
	v_add_f32_e32 v38, v38, v40
	v_pk_mul_f32 v[42:43], v[16:17], v[16:17]
	v_add_f32_e32 v38, v38, v41
	v_pk_fma_f32 v[18:19], v[110:111], v[44:45], v[18:19] neg_lo:[1,0,0] neg_hi:[1,0,0]
	v_add_f32_e32 v38, v38, v42
	v_pk_mul_f32 v[44:45], v[18:19], v[18:19]
	v_add_f32_e32 v38, v38, v43
	v_add_f32_e32 v38, v38, v44
	v_pk_mul_f32 v[24:25], v[20:21], v[20:21]
	v_add_f32_e32 v38, v38, v45
	v_add_f32_e32 v24, v38, v24
	v_pk_mul_f32 v[26:27], v[22:23], v[22:23]
	v_add_f32_e32 v24, v24, v25
	v_add_f32_e32 v24, v24, v26
	v_add_f32_e32 v24, v24, v27
	ds_swizzle_b32 v25, v24 offset:swizzle(SWAP,1)
	s_mov_b32 s0, 0x800000
	v_ashrrev_i32_e32 v51, 31, v50
	s_waitcnt lgkmcnt(0)
	v_add_f32_e32 v24, v24, v25
	ds_swizzle_b32 v25, v24 offset:swizzle(SWAP,2)
	s_waitcnt lgkmcnt(0)
	v_add_f32_e32 v24, v24, v25
	v_mov_b32_e32 v25, 0x3727c5ac
	v_fmamk_f32 v24, v24, 0x3c800000, v25
	v_mul_f32_e32 v25, 0x4b800000, v24
	v_cmp_gt_f32_e32 vcc, s0, v24
	s_add_u32 s0, s37, s33
	s_addc_u32 s1, 0, 0
	v_cndmask_b32_e32 v24, v24, v25, vcc
	v_rsq_f32_e32 v24, v24
	s_nop 0
	v_mul_f32_e32 v25, 0x45800000, v24
	v_cndmask_b32_e32 v24, v24, v25, vcc
	v_mul_f32_e32 v24, v147, v24
	v_pk_mul_f32 v[16:17], v[16:17], v[24:25] op_sel_hi:[1,0]
	v_pk_mul_f32 v[18:19], v[18:19], v[24:25] op_sel_hi:[1,0]
	v_pk_mul_f32 v[26:27], v[28:29], v[24:25] op_sel_hi:[1,0]
	v_pk_mul_f32 v[28:29], v[30:31], v[24:25] op_sel_hi:[1,0]
	v_pk_mul_f32 v[30:31], v[34:35], v[24:25] op_sel_hi:[1,0]
	v_pk_mul_f32 v[34:35], v[36:37], v[24:25] op_sel_hi:[1,0]
	v_pk_mul_f32 v[20:21], v[20:21], v[24:25] op_sel_hi:[1,0]
	s_waitcnt vmcnt(5)
	v_pk_mul_f32 v[0:1], v[74:75], v[26:27]
	s_waitcnt vmcnt(4)
	v_pk_mul_f32 v[4:5], v[78:79], v[16:17]
	v_pk_mul_f32 v[16:17], v[22:23], v[24:25] op_sel_hi:[1,0]
	v_pk_mul_f32 v[6:7], v[80:81], v[18:19]
	s_waitcnt vmcnt(2)
	v_pk_mul_f32 v[14:15], v[16:17], v[88:89]
	v_lshl_add_u64 v[16:17], s[0:1], 0, v[50:51]
	v_readlane_b32 s0, v250, 15
	v_lshlrev_b64 v[16:17], 11, v[16:17]
	v_readlane_b32 s12, v250, 27
	v_readlane_b32 s13, v250, 28
	v_readlane_b32 s1, v250, 16
	v_lshlrev_b32_e32 v18, 1, v52
	v_lshl_add_u64 v[16:17], s[12:13], 0, v[16:17]
	v_lshl_add_u64 v[16:17], v[16:17], 0, s[34:35]
	v_mov_b32_e32 v19, v65
	v_lshl_add_u64 v[16:17], v[16:17], 0, v[18:19]
	s_mov_b64 s[0:1], 0x2000200
	v_pk_mul_f32 v[2:3], v[76:77], v[28:29]
	v_pk_mul_f32 v[8:9], v[82:83], v[30:31]
	v_lshl_add_u64 v[18:19], v[16:17], 0, s[0:1]
	s_brev_b32 s0, 64
	v_pk_mul_f32 v[10:11], v[34:35], v[84:85]
	v_cvt_pk_bf16_f32 v0, v0, v1
	v_cvt_pk_bf16_f32 v1, v2, v3
	v_cvt_pk_bf16_f32 v2, v8, v9
	v_add_co_u32_e32 v8, vcc, s0, v16
	v_pk_mul_f32 v[12:13], v[86:87], v[20:21]
	v_cvt_pk_bf16_f32 v3, v10, v11
	v_addc_co_u32_e32 v9, vcc, 0, v17, vcc
	global_store_dwordx4 v[8:9], v[0:3], off offset:512
	s_mov_b64 s[0:1], 0
	v_readlane_b32 s2, v250, 17
	v_cvt_pk_bf16_f32 v0, v4, v5
	v_cvt_pk_bf16_f32 v1, v6, v7
	v_cvt_pk_bf16_f32 v2, v12, v13
	v_cvt_pk_bf16_f32 v3, v14, v15
	v_readlane_b32 s3, v250, 18
	v_readlane_b32 s4, v250, 19
	v_readlane_b32 s5, v250, 20
	v_readlane_b32 s6, v250, 21
	v_readlane_b32 s7, v250, 22
	v_readlane_b32 s8, v250, 23
	v_readlane_b32 s9, v250, 24
	v_readlane_b32 s10, v250, 25
	v_readlane_b32 s11, v250, 26
	v_readlane_b32 s14, v250, 29
	v_readlane_b32 s15, v250, 30
	global_store_dwordx4 v[18:19], v[0:3], off offset:16
	s_barrier
